# baseline (speedup 1.0000x reference)
; template <class Epi, class Sched, bool ALIGN_EPI = false, bool SP2 = false>
; __device__ __forceinline__ void gemm_phase(PG8_LAS unsigned char* lds, const Gemm g, const Sched& S, const Epi& E, int wid_s_) {
;     ...
; #pragma unroll
;         for (int a = 0; a < 2; ++a)
; #pragma unroll
;             for (int b = 0; b < 2; ++b)
; #pragma unroll
;                 for (int m = 0; m < 4; ++m)
; #pragma unroll
;                     for (int n = 0; n < 2; ++n) acc[a][b][m][n] = (f32x4){0.f, 0.f, 0.f, 0.f};
;         cur = nxt; cA = nA; cB = nB; ++ui;
.LBB0_382:
	v_mov_b32_e32 v125, 0
	s_andn2_b64 vcc, exec, s[18:19]
	v_mov_b32_e32 v124, v125
	v_mov_b32_e32 v123, v125
	v_mov_b32_e32 v122, v125
	v_mov_b32_e32 v121, v125
	v_mov_b32_e32 v120, v125
	v_mov_b32_e32 v119, v125
	v_mov_b32_e32 v118, v125
	v_mov_b32_e32 v95, v125
	v_mov_b32_e32 v94, v125
	v_mov_b32_e32 v93, v125
	v_mov_b32_e32 v92, v125
	v_mov_b32_e32 v87, v125
	v_mov_b32_e32 v86, v125
	v_mov_b32_e32 v85, v125
	v_mov_b32_e32 v84, v125
	v_mov_b32_e32 v63, v125
	v_mov_b32_e32 v62, v125
	v_mov_b32_e32 v61, v125
	v_mov_b32_e32 v60, v125
	v_mov_b32_e32 v55, v125
	v_mov_b32_e32 v54, v125
	v_mov_b32_e32 v53, v125
	v_mov_b32_e32 v52, v125
	v_mov_b32_e32 v31, v125
	v_mov_b32_e32 v30, v125
	v_mov_b32_e32 v29, v125
	v_mov_b32_e32 v28, v125
	v_mov_b32_e32 v23, v125
	v_mov_b32_e32 v22, v125
	v_mov_b32_e32 v21, v125
	v_mov_b32_e32 v20, v125
	v_mov_b32_e32 v113, v125
	v_mov_b32_e32 v112, v125
	v_mov_b32_e32 v111, v125
	v_mov_b32_e32 v110, v125
	v_mov_b32_e32 v105, v125
	v_mov_b32_e32 v104, v125
	v_mov_b32_e32 v103, v125
	v_mov_b32_e32 v102, v125
	v_mov_b32_e32 v79, v125
	v_mov_b32_e32 v78, v125
	v_mov_b32_e32 v77, v125
	v_mov_b32_e32 v76, v125
	v_mov_b32_e32 v71, v125
	v_mov_b32_e32 v70, v125
	v_mov_b32_e32 v69, v125
	v_mov_b32_e32 v68, v125
	v_mov_b32_e32 v47, v125
	v_mov_b32_e32 v46, v125
	v_mov_b32_e32 v45, v125
	v_mov_b32_e32 v44, v125
	v_mov_b32_e32 v39, v125
	v_mov_b32_e32 v38, v125
	v_mov_b32_e32 v37, v125
	v_mov_b32_e32 v36, v125
	v_mov_b32_e32 v15, v125
	v_mov_b32_e32 v14, v125
	v_mov_b32_e32 v13, v125
	v_mov_b32_e32 v12, v125
	v_mov_b32_e32 v7, v125
	v_mov_b32_e32 v6, v125
	v_mov_b32_e32 v5, v125
	v_mov_b32_e32 v4, v125
	v_mov_b32_e32 v129, v125
	v_mov_b32_e32 v128, v125
	v_mov_b32_e32 v127, v125
	v_mov_b32_e32 v126, v125
	v_mov_b32_e32 v117, v125
	v_mov_b32_e32 v116, v125
	v_mov_b32_e32 v115, v125
	v_mov_b32_e32 v114, v125
	v_mov_b32_e32 v91, v125
	v_mov_b32_e32 v90, v125
	v_mov_b32_e32 v89, v125
	v_mov_b32_e32 v88, v125
	v_mov_b32_e32 v83, v125
	v_mov_b32_e32 v82, v125
	v_mov_b32_e32 v81, v125
	v_mov_b32_e32 v80, v125
	v_mov_b32_e32 v59, v125
	v_mov_b32_e32 v58, v125
	v_mov_b32_e32 v57, v125
	v_mov_b32_e32 v56, v125
	v_mov_b32_e32 v51, v125
	v_mov_b32_e32 v50, v125
	v_mov_b32_e32 v49, v125
	v_mov_b32_e32 v48, v125
	v_mov_b32_e32 v27, v125
	v_mov_b32_e32 v26, v125
	v_mov_b32_e32 v25, v125
	v_mov_b32_e32 v24, v125
	v_mov_b32_e32 v19, v125
	v_mov_b32_e32 v18, v125
	v_mov_b32_e32 v17, v125
	v_mov_b32_e32 v16, v125
	v_mov_b32_e32 v109, v125
	v_mov_b32_e32 v108, v125
	v_mov_b32_e32 v107, v125
	v_mov_b32_e32 v106, v125
	v_mov_b32_e32 v101, v125
	v_mov_b32_e32 v100, v125
	v_mov_b32_e32 v99, v125
	v_mov_b32_e32 v98, v125
	v_mov_b32_e32 v75, v125
	v_mov_b32_e32 v74, v125
	v_mov_b32_e32 v73, v125
	v_mov_b32_e32 v72, v125
	v_mov_b32_e32 v67, v125
	v_mov_b32_e32 v66, v125
	v_mov_b32_e32 v65, v125
	v_mov_b32_e32 v64, v125
	v_mov_b32_e32 v43, v125
	v_mov_b32_e32 v42, v125
	v_mov_b32_e32 v41, v125
	v_mov_b32_e32 v40, v125
	v_mov_b32_e32 v35, v125
	v_mov_b32_e32 v34, v125
	v_mov_b32_e32 v33, v125
	v_mov_b32_e32 v32, v125
	v_mov_b32_e32 v11, v125
	v_mov_b32_e32 v10, v125
	v_mov_b32_e32 v9, v125
	v_mov_b32_e32 v8, v125
	v_mov_b32_e32 v3, v125
	v_mov_b32_e32 v2, v125
	v_mov_b32_e32 v1, v125
	v_mov_b32_e32 v0, v125
	s_cbranch_vccnz .LBB0_386
	s_add_u32 s80, s24, 0x100
	s_addc_u32 s81, s25, 0
	s_add_u32 s24, s48, 0x80
	v_mov_b32_e32 v0, 0
	s_addc_u32 s25, s49, 0
	s_mov_b32 s48, 0
	v_mov_b32_e32 v1, v0
	v_mov_b32_e32 v2, v0
	v_mov_b32_e32 v3, v0
	v_mov_b32_e32 v8, v0
	v_mov_b32_e32 v9, v0
	v_mov_b32_e32 v10, v0
	v_mov_b32_e32 v11, v0
	v_mov_b32_e32 v32, v0
	v_mov_b32_e32 v33, v0
	v_mov_b32_e32 v34, v0
	v_mov_b32_e32 v35, v0
	v_mov_b32_e32 v40, v0
	v_mov_b32_e32 v41, v0
	v_mov_b32_e32 v42, v0
	v_mov_b32_e32 v43, v0
	v_mov_b32_e32 v64, v0
	v_mov_b32_e32 v65, v0
	v_mov_b32_e32 v66, v0
	v_mov_b32_e32 v67, v0
	v_mov_b32_e32 v72, v0
	v_mov_b32_e32 v73, v0
	v_mov_b32_e32 v74, v0
	v_mov_b32_e32 v75, v0
	v_mov_b32_e32 v98, v0
	v_mov_b32_e32 v99, v0
	v_mov_b32_e32 v100, v0
	v_mov_b32_e32 v101, v0
	v_mov_b32_e32 v106, v0
	v_mov_b32_e32 v107, v0
	v_mov_b32_e32 v108, v0
	v_mov_b32_e32 v109, v0
	v_mov_b32_e32 v16, v0
	v_mov_b32_e32 v17, v0
	v_mov_b32_e32 v18, v0
	v_mov_b32_e32 v19, v0
	v_mov_b32_e32 v24, v0
	v_mov_b32_e32 v25, v0
	v_mov_b32_e32 v26, v0
	v_mov_b32_e32 v27, v0
	v_mov_b32_e32 v48, v0
	v_mov_b32_e32 v49, v0
	v_mov_b32_e32 v50, v0
	v_mov_b32_e32 v51, v0
	v_mov_b32_e32 v56, v0
	v_mov_b32_e32 v57, v0
	v_mov_b32_e32 v58, v0
	v_mov_b32_e32 v59, v0
	v_mov_b32_e32 v80, v0
	v_mov_b32_e32 v81, v0
	v_mov_b32_e32 v82, v0
	v_mov_b32_e32 v83, v0
	v_mov_b32_e32 v88, v0
	v_mov_b32_e32 v89, v0
	v_mov_b32_e32 v90, v0
	v_mov_b32_e32 v91, v0
	v_mov_b32_e32 v114, v0
	v_mov_b32_e32 v115, v0
	v_mov_b32_e32 v116, v0
	v_mov_b32_e32 v117, v0
	v_mov_b32_e32 v126, v0
	v_mov_b32_e32 v127, v0
	v_mov_b32_e32 v128, v0
	v_mov_b32_e32 v129, v0
	v_mov_b32_e32 v4, v0
	v_mov_b32_e32 v5, v0
	v_mov_b32_e32 v6, v0
	v_mov_b32_e32 v7, v0
	v_mov_b32_e32 v12, v0
	v_mov_b32_e32 v13, v0
	v_mov_b32_e32 v14, v0
	v_mov_b32_e32 v15, v0
	v_mov_b32_e32 v36, v0
	v_mov_b32_e32 v37, v0
	v_mov_b32_e32 v38, v0
	v_mov_b32_e32 v39, v0
	v_mov_b32_e32 v44, v0
	v_mov_b32_e32 v45, v0
	v_mov_b32_e32 v46, v0
	v_mov_b32_e32 v47, v0
	v_mov_b32_e32 v68, v0
	v_mov_b32_e32 v69, v0
	v_mov_b32_e32 v70, v0
	v_mov_b32_e32 v71, v0
	v_mov_b32_e32 v76, v0
	v_mov_b32_e32 v77, v0
	v_mov_b32_e32 v78, v0
	v_mov_b32_e32 v79, v0
	v_mov_b32_e32 v102, v0
	v_mov_b32_e32 v103, v0
	v_mov_b32_e32 v104, v0
	v_mov_b32_e32 v105, v0
	v_mov_b32_e32 v110, v0
	v_mov_b32_e32 v111, v0
	v_mov_b32_e32 v112, v0
	v_mov_b32_e32 v113, v0
	v_mov_b32_e32 v20, v0
	v_mov_b32_e32 v21, v0
	v_mov_b32_e32 v22, v0
	v_mov_b32_e32 v23, v0
	v_mov_b32_e32 v28, v0
	v_mov_b32_e32 v29, v0
	v_mov_b32_e32 v30, v0
	v_mov_b32_e32 v31, v0
	v_mov_b32_e32 v52, v0
	v_mov_b32_e32 v53, v0
	v_mov_b32_e32 v54, v0
	v_mov_b32_e32 v55, v0
	v_mov_b32_e32 v60, v0
	v_mov_b32_e32 v61, v0
	v_mov_b32_e32 v62, v0
	v_mov_b32_e32 v63, v0
	v_mov_b32_e32 v84, v0
	v_mov_b32_e32 v85, v0
	v_mov_b32_e32 v86, v0
	v_mov_b32_e32 v87, v0
	v_mov_b32_e32 v92, v0
	v_mov_b32_e32 v93, v0
	v_mov_b32_e32 v94, v0
	v_mov_b32_e32 v95, v0
	v_mov_b32_e32 v118, v0
	v_mov_b32_e32 v119, v0
	v_mov_b32_e32 v120, v0
	v_mov_b32_e32 v121, v0
	v_mov_b32_e32 v122, v0
	v_mov_b32_e32 v123, v0
	v_mov_b32_e32 v124, v0
	v_mov_b32_e32 v125, v0
	v_add_u32_e32 v150, s10, v154
	v_add_u32_e32 v151, s10, v158
	v_add_u32_e32 v188, s10, v152
	v_add_u32_e32 v189, s10, v156
	v_add_u32_e32 v192, s42, v154
	v_add_u32_e32 v193, s42, v158
	v_add_u32_e32 v228, s42, v152
	v_add_u32_e32 v229, s42, v156
	v_add_u32_e32 v226, s42, v150
	v_add_u32_e32 v227, s42, v151
; #define PG8_STAGE(bufoff, gbase, voff) do { _Pragma("unroll") for (int _i = 0; _i < 2; ++_i) \
;         __builtin_amdgcn_global_load_lds((const unsigned*)((const char*)(gbase) + (voff)[_i]), (PG8_LAS unsigned*)(lds + (bufoff) + ldsw + _i * 8192), 16, 0, 0); } while (0)
; #define PG8_LDA(dst, b, h) do { _Pragma("unroll") for (int m = 0; m < 4; ++m) _Pragma("unroll") for (int k = 0; k < 2; ++k) dst[m][k] = *(const PG8_LAS bf16x8*)(lds + PG8_SA(b, h) + aoff + m * 2048 + k * 1024); } while (0)
; #define PG8_LDB(dst, b, h) do { _Pragma("unroll") for (int n = 0; n < 2; ++n) _Pragma("unroll") for (int k = 0; k < 2; ++k) dst[n][k] = *(const PG8_LAS bf16x8*)(lds + PG8_SB(b, h) + boff + n * 2048 + k * 1024); } while (0)
; #define PG8_MMA(ai, bj, At, Bt) do { __builtin_amdgcn_s_setprio(1); _Pragma("unroll") for (int m = 0; m < 4; ++m) _Pragma("unroll") for (int n = 0; n < 2; ++n) _Pragma("unroll") for (int k = 0; k < 2; ++k) \
;         acc[ai][bj][m][n] = __builtin_amdgcn_mfma_f32_16x16x32_bf16(Bt[n][k], At[m][k], acc[ai][bj][m][n], 0, 0, 0); __builtin_amdgcn_s_setprio(0); } while (0)
; #define PG8_WAIT_V(n) asm volatile("s_waitcnt vmcnt(" #n ")" ::: "memory")
; #define PG8_WAIT_L(n) asm volatile("s_waitcnt lgkmcnt(" #n ")" ::: "memory")
; #define PG8_BAR __builtin_amdgcn_s_barrier()
; #define PG8_SCHED __builtin_amdgcn_sched_barrier(0)
; template <class Epi, class Sched, bool ALIGN_EPI = false, bool SP2 = false>
; __device__ __forceinline__ void gemm_phase(PG8_LAS unsigned char* lds, const Gemm g, const Sched& S, const Epi& E, int wid_s_) {
;     ...
;             PG8_LDB(B0, 0, 0); PG8_LDB(B1, 0, 1); PG8_SCHED; PG8_LDA(At, 0, 0); PG8_STAGE(PG8_SA(1, 1), a1 + hstep, voffA);
;             PG8_WAIT_V(8); PG8_WAIT_L(0); PG8_BAR; PG8_MMA(0, 0, At, B0); PG8_MMA(0, 1, At, B1); PG8_BAR; PG8_SCHED;
;             PG8_LDA(At, 0, 1); PG8_STAGE(PG8_SB(0, 0), b2, voffB); PG8_STAGE(PG8_SB(0, 1), b2 + hstep, voffB); PG8_STAGE(PG8_SA(0, 0), a2, voffA);
;             PG8_WAIT_V(8); PG8_WAIT_L(0); PG8_BAR; PG8_MMA(1, 0, At, B0); PG8_MMA(1, 1, At, B1); PG8_BAR; PG8_SCHED;
.LBB0_384:
	s_add_i32 vcc_lo, s48, 2
	s_add_u32 s78, s24, 0x80
	s_addc_u32 s49, s25, 0
	s_add_i32 vcc_hi, 16, 0x10000
	s_cmp_eq_u32 s87, s48
	s_cselect_b32 s49, s3, s49
	s_cselect_b32 s48, s2, s78
	v_add_u32_e32 v96, vcc_hi, v147
	s_cselect_b32 s79, s23, s81
	s_cselect_b32 s78, s22, s80
	s_add_i32 s40, 16, 0x14000
	ds_read_b128 v[130:133], v96
	ds_read_b128 v[134:137], v96 offset:1024
	ds_read_b128 v[138:141], v96 offset:2048
	ds_read_b128 v[142:145], v96 offset:3072
	v_add_u32_e32 v96, s40, v147
	ds_read_b128 v[168:171], v96
	ds_read_b128 v[172:175], v96 offset:1024
	ds_read_b128 v[176:179], v96 offset:2048
	ds_read_b128 v[180:183], v96 offset:3072
	s_add_i32 m0, s51, 0xc000
	ds_read_b128 v[194:197], v148
	ds_read_b128 v[198:201], v148 offset:1024
	ds_read_b128 v[202:205], v148 offset:2048
	ds_read_b128 v[206:209], v148 offset:3072
	ds_read_b128 v[210:213], v148 offset:4096
	ds_read_b128 v[214:217], v148 offset:5120
	ds_read_b128 v[218:221], v148 offset:6144
	ds_read_b128 v[222:225], v148 offset:7168
	global_load_lds_dwordx4 v166, s[24:25]
	s_add_i32 m0, s51, 0xe000
	s_nop 0
	global_load_lds_dwordx4 v164, s[24:25]
	s_waitcnt vmcnt(8)
	s_waitcnt lgkmcnt(0)
	s_barrier
	s_setprio 1
	s_waitcnt lgkmcnt(0)
	v_mfma_f32_16x16x32_bf16 v[122:125], v[130:133], v[194:197], v[122:125]
	v_mfma_f32_16x16x32_bf16 v[118:121], v[138:141], v[194:197], v[118:121]
	v_mfma_f32_16x16x32_bf16 v[92:95], v[130:133], v[202:205], v[92:95]
	v_mfma_f32_16x16x32_bf16 v[84:87], v[138:141], v[202:205], v[84:87]
	v_mfma_f32_16x16x32_bf16 v[60:63], v[130:133], v[210:213], v[60:63]
	v_mfma_f32_16x16x32_bf16 v[52:55], v[138:141], v[210:213], v[52:55]
	v_mfma_f32_16x16x32_bf16 v[28:31], v[130:133], v[218:221], v[28:31]
	v_mfma_f32_16x16x32_bf16 v[20:23], v[138:141], v[218:221], v[20:23]
	v_mfma_f32_16x16x32_bf16 v[122:125], v[134:137], v[198:201], v[122:125]
	v_mfma_f32_16x16x32_bf16 v[118:121], v[142:145], v[198:201], v[118:121]
	v_mfma_f32_16x16x32_bf16 v[92:95], v[134:137], v[206:209], v[92:95]
	v_mfma_f32_16x16x32_bf16 v[84:87], v[142:145], v[206:209], v[84:87]
	v_mfma_f32_16x16x32_bf16 v[60:63], v[134:137], v[214:217], v[60:63]
	v_mfma_f32_16x16x32_bf16 v[52:55], v[142:145], v[214:217], v[52:55]
	v_mfma_f32_16x16x32_bf16 v[28:31], v[134:137], v[222:225], v[28:31]
	v_mfma_f32_16x16x32_bf16 v[20:23], v[142:145], v[222:225], v[20:23]
	s_setprio 0
	s_setprio 1
	v_mfma_f32_16x16x32_bf16 v[110:113], v[168:171], v[194:197], v[110:113]
	v_mfma_f32_16x16x32_bf16 v[102:105], v[176:179], v[194:197], v[102:105]
	v_mfma_f32_16x16x32_bf16 v[76:79], v[168:171], v[202:205], v[76:79]
	v_mfma_f32_16x16x32_bf16 v[68:71], v[176:179], v[202:205], v[68:71]
	v_mfma_f32_16x16x32_bf16 v[44:47], v[168:171], v[210:213], v[44:47]
	v_mfma_f32_16x16x32_bf16 v[36:39], v[176:179], v[210:213], v[36:39]
	v_mfma_f32_16x16x32_bf16 v[12:15], v[168:171], v[218:221], v[12:15]
	v_mfma_f32_16x16x32_bf16 v[4:7], v[176:179], v[218:221], v[4:7]
	v_mfma_f32_16x16x32_bf16 v[110:113], v[172:175], v[198:201], v[110:113]
	v_mfma_f32_16x16x32_bf16 v[102:105], v[180:183], v[198:201], v[102:105]
	v_mfma_f32_16x16x32_bf16 v[76:79], v[172:175], v[206:209], v[76:79]
	v_mfma_f32_16x16x32_bf16 v[68:71], v[180:183], v[206:209], v[68:71]
	v_mfma_f32_16x16x32_bf16 v[44:47], v[172:175], v[214:217], v[44:47]
	v_mfma_f32_16x16x32_bf16 v[36:39], v[180:183], v[214:217], v[36:39]
	v_mfma_f32_16x16x32_bf16 v[12:15], v[172:175], v[222:225], v[12:15]
	v_mfma_f32_16x16x32_bf16 v[4:7], v[180:183], v[222:225], v[4:7]
	s_setprio 0
	s_barrier
	s_add_i32 vcc_hi, vcc_hi, s50
	s_mov_b32 m0, vcc_hi
	ds_read_b128 v[194:197], v148 offset:16384
	ds_read_b128 v[198:201], v148 offset:17408
	ds_read_b128 v[202:205], v148 offset:18432
	ds_read_b128 v[206:209], v148 offset:19456
	ds_read_b128 v[210:213], v148 offset:20480
	ds_read_b128 v[214:217], v148 offset:21504
	ds_read_b128 v[218:221], v148 offset:22528
	ds_read_b128 v[222:225], v148 offset:23552
	global_load_lds_dwordx4 v154, s[78:79]
	s_add_i32 m0, vcc_hi, 0x2000
	s_add_i32 s40, s40, s50
	global_load_lds_dwordx4 v158, s[78:79]
	s_mov_b32 m0, s40
	s_nop 0
	global_load_lds_dwordx4 v150, s[78:79]
	s_add_i32 m0, s40, 0x2000
	s_nop 0
	global_load_lds_dwordx4 v151, s[78:79]
	s_mov_b32 m0, s51
	s_nop 0
	global_load_lds_dwordx4 v152, s[48:49]
	s_mov_b32 m0, s82
	s_nop 0
	global_load_lds_dwordx4 v156, s[48:49]
	s_waitcnt vmcnt(8)
	s_waitcnt lgkmcnt(0)
	s_barrier
	s_setprio 1
	s_waitcnt lgkmcnt(0)
	v_mfma_f32_16x16x32_bf16 v[126:129], v[130:133], v[194:197], v[126:129]
	v_mfma_f32_16x16x32_bf16 v[114:117], v[138:141], v[194:197], v[114:117]
	v_mfma_f32_16x16x32_bf16 v[88:91], v[130:133], v[202:205], v[88:91]
	v_mfma_f32_16x16x32_bf16 v[80:83], v[138:141], v[202:205], v[80:83]
	v_mfma_f32_16x16x32_bf16 v[56:59], v[130:133], v[210:213], v[56:59]
	v_mfma_f32_16x16x32_bf16 v[48:51], v[138:141], v[210:213], v[48:51]
	v_mfma_f32_16x16x32_bf16 v[24:27], v[130:133], v[218:221], v[24:27]
	v_mfma_f32_16x16x32_bf16 v[16:19], v[138:141], v[218:221], v[16:19]
	v_mfma_f32_16x16x32_bf16 v[126:129], v[134:137], v[198:201], v[126:129]
	v_mfma_f32_16x16x32_bf16 v[114:117], v[142:145], v[198:201], v[114:117]
	v_mfma_f32_16x16x32_bf16 v[88:91], v[134:137], v[206:209], v[88:91]
	v_mfma_f32_16x16x32_bf16 v[80:83], v[142:145], v[206:209], v[80:83]
	v_mfma_f32_16x16x32_bf16 v[56:59], v[134:137], v[214:217], v[56:59]
	v_mfma_f32_16x16x32_bf16 v[48:51], v[142:145], v[214:217], v[48:51]
	v_mfma_f32_16x16x32_bf16 v[24:27], v[134:137], v[222:225], v[24:27]
	v_mfma_f32_16x16x32_bf16 v[16:19], v[142:145], v[222:225], v[16:19]
	s_setprio 0
	s_setprio 1
	v_mfma_f32_16x16x32_bf16 v[106:109], v[168:171], v[194:197], v[106:109]
	v_mfma_f32_16x16x32_bf16 v[98:101], v[176:179], v[194:197], v[98:101]
	v_mfma_f32_16x16x32_bf16 v[72:75], v[168:171], v[202:205], v[72:75]
	v_mfma_f32_16x16x32_bf16 v[64:67], v[176:179], v[202:205], v[64:67]
	v_mfma_f32_16x16x32_bf16 v[40:43], v[168:171], v[210:213], v[40:43]
	v_mfma_f32_16x16x32_bf16 v[32:35], v[176:179], v[210:213], v[32:35]
	v_mfma_f32_16x16x32_bf16 v[8:11], v[168:171], v[218:221], v[8:11]
	v_mfma_f32_16x16x32_bf16 v[0:3], v[176:179], v[218:221], v[0:3]
	v_mfma_f32_16x16x32_bf16 v[106:109], v[172:175], v[198:201], v[106:109]
	v_mfma_f32_16x16x32_bf16 v[98:101], v[180:183], v[198:201], v[98:101]
	v_mfma_f32_16x16x32_bf16 v[72:75], v[172:175], v[206:209], v[72:75]
	v_mfma_f32_16x16x32_bf16 v[64:67], v[180:183], v[206:209], v[64:67]
	v_mfma_f32_16x16x32_bf16 v[40:43], v[172:175], v[214:217], v[40:43]
	v_mfma_f32_16x16x32_bf16 v[32:35], v[180:183], v[214:217], v[32:35]
	v_mfma_f32_16x16x32_bf16 v[8:11], v[172:175], v[222:225], v[8:11]
	v_mfma_f32_16x16x32_bf16 v[0:3], v[180:183], v[222:225], v[0:3]
	s_setprio 0
	s_barrier
; #define PG8_STAGE(bufoff, gbase, voff) do { _Pragma("unroll") for (int _i = 0; _i < 2; ++_i) \
;         __builtin_amdgcn_global_load_lds((const unsigned*)((const char*)(gbase) + (voff)[_i]), (PG8_LAS unsigned*)(lds + (bufoff) + ldsw + _i * 8192), 16, 0, 0); } while (0)
; #define PG8_LDA(dst, b, h) do { _Pragma("unroll") for (int m = 0; m < 4; ++m) _Pragma("unroll") for (int k = 0; k < 2; ++k) dst[m][k] = *(const PG8_LAS bf16x8*)(lds + PG8_SA(b, h) + aoff + m * 2048 + k * 1024); } while (0)
; #define PG8_LDB(dst, b, h) do { _Pragma("unroll") for (int n = 0; n < 2; ++n) _Pragma("unroll") for (int k = 0; k < 2; ++k) dst[n][k] = *(const PG8_LAS bf16x8*)(lds + PG8_SB(b, h) + boff + n * 2048 + k * 1024); } while (0)
; #define PG8_MMA(ai, bj, At, Bt) do { __builtin_amdgcn_s_setprio(1); _Pragma("unroll") for (int m = 0; m < 4; ++m) _Pragma("unroll") for (int n = 0; n < 2; ++n) _Pragma("unroll") for (int k = 0; k < 2; ++k) \
;         acc[ai][bj][m][n] = __builtin_amdgcn_mfma_f32_16x16x32_bf16(Bt[n][k], At[m][k], acc[ai][bj][m][n], 0, 0, 0); __builtin_amdgcn_s_setprio(0); } while (0)
; #define PG8_WAIT_V(n) asm volatile("s_waitcnt vmcnt(" #n ")" ::: "memory")
; #define PG8_WAIT_L(n) asm volatile("s_waitcnt lgkmcnt(" #n ")" ::: "memory")
; #define PG8_BAR __builtin_amdgcn_s_barrier()
; #define PG8_SCHED __builtin_amdgcn_sched_barrier(0)
; template <class Epi, class Sched, bool ALIGN_EPI = false, bool SP2 = false>
; __device__ __forceinline__ void gemm_phase(PG8_LAS unsigned char* lds, const Gemm g, const Sched& S, const Epi& E, int wid_s_) {
;     ...
;         for (int t = 0; t < nt; t += 2) {
;     ...
;             PG8_LDB(B0, 1, 0); PG8_LDB(B1, 1, 1); PG8_SCHED; PG8_LDA(At, 1, 0); PG8_STAGE(PG8_SA(0, 1), a2 + hstep, voffA);
;             PG8_WAIT_V(8); PG8_WAIT_L(0); PG8_BAR; PG8_MMA(0, 0, At, B0); PG8_MMA(0, 1, At, B1); PG8_BAR; PG8_SCHED;
;             PG8_LDA(At, 1, 1); PG8_STAGE(PG8_SB(1, 0), b3, voffB); PG8_STAGE(PG8_SB(1, 1), b3 + hstep, voffB); PG8_STAGE(PG8_SA(1, 0), a3, voffA);
;             PG8_WAIT_V(8); PG8_WAIT_L(0); PG8_BAR; PG8_MMA(1, 0, At, B0); PG8_MMA(1, 1, At, B1); PG8_BAR; PG8_SCHED;
	s_add_i32 s40, 16, 0x18000
	v_add_u32_e32 v96, s40, v147
	ds_read_b128 v[130:133], v96
	ds_read_b128 v[134:137], v96 offset:1024
	ds_read_b128 v[138:141], v96 offset:2048
	ds_read_b128 v[142:145], v96 offset:3072
	v_add_u32_e32 v96, 0x1c010, v147
	ds_read_b128 v[168:171], v96
	ds_read_b128 v[172:175], v96 offset:1024
	ds_read_b128 v[176:179], v96 offset:2048
	ds_read_b128 v[180:183], v96 offset:3072
	s_mov_b32 m0, s83
	ds_read_b128 v[194:197], v148 offset:32768
	ds_read_b128 v[198:201], v148 offset:33792
	ds_read_b128 v[202:205], v148 offset:34816
	ds_read_b128 v[206:209], v148 offset:35840
	ds_read_b128 v[210:213], v148 offset:36864
	ds_read_b128 v[214:217], v148 offset:37888
	ds_read_b128 v[218:221], v148 offset:38912
	ds_read_b128 v[222:225], v148 offset:39936
	global_load_lds_dwordx4 v188, s[48:49]
	s_mov_b32 m0, s84
	s_nop 0
	global_load_lds_dwordx4 v189, s[48:49]
	s_waitcnt vmcnt(8)
	s_waitcnt lgkmcnt(0)
	s_barrier
	s_setprio 1
	s_waitcnt lgkmcnt(0)
	v_mfma_f32_16x16x32_bf16 v[122:125], v[130:133], v[194:197], v[122:125]
	v_mfma_f32_16x16x32_bf16 v[118:121], v[138:141], v[194:197], v[118:121]
	v_mfma_f32_16x16x32_bf16 v[92:95], v[130:133], v[202:205], v[92:95]
	v_mfma_f32_16x16x32_bf16 v[84:87], v[138:141], v[202:205], v[84:87]
	v_mfma_f32_16x16x32_bf16 v[60:63], v[130:133], v[210:213], v[60:63]
	v_mfma_f32_16x16x32_bf16 v[52:55], v[138:141], v[210:213], v[52:55]
	v_mfma_f32_16x16x32_bf16 v[28:31], v[130:133], v[218:221], v[28:31]
	v_mfma_f32_16x16x32_bf16 v[20:23], v[138:141], v[218:221], v[20:23]
	v_mfma_f32_16x16x32_bf16 v[122:125], v[134:137], v[198:201], v[122:125]
	v_mfma_f32_16x16x32_bf16 v[118:121], v[142:145], v[198:201], v[118:121]
	v_mfma_f32_16x16x32_bf16 v[92:95], v[134:137], v[206:209], v[92:95]
	v_mfma_f32_16x16x32_bf16 v[84:87], v[142:145], v[206:209], v[84:87]
	v_mfma_f32_16x16x32_bf16 v[60:63], v[134:137], v[214:217], v[60:63]
	v_mfma_f32_16x16x32_bf16 v[52:55], v[142:145], v[214:217], v[52:55]
	v_mfma_f32_16x16x32_bf16 v[28:31], v[134:137], v[222:225], v[28:31]
	v_mfma_f32_16x16x32_bf16 v[20:23], v[142:145], v[222:225], v[20:23]
	s_setprio 0
	s_setprio 1
	v_mfma_f32_16x16x32_bf16 v[110:113], v[168:171], v[194:197], v[110:113]
	v_mfma_f32_16x16x32_bf16 v[102:105], v[176:179], v[194:197], v[102:105]
	v_mfma_f32_16x16x32_bf16 v[76:79], v[168:171], v[202:205], v[76:79]
	v_mfma_f32_16x16x32_bf16 v[68:71], v[176:179], v[202:205], v[68:71]
	v_mfma_f32_16x16x32_bf16 v[44:47], v[168:171], v[210:213], v[44:47]
	v_mfma_f32_16x16x32_bf16 v[36:39], v[176:179], v[210:213], v[36:39]
	v_mfma_f32_16x16x32_bf16 v[12:15], v[168:171], v[218:221], v[12:15]
	v_mfma_f32_16x16x32_bf16 v[4:7], v[176:179], v[218:221], v[4:7]
	v_mfma_f32_16x16x32_bf16 v[110:113], v[172:175], v[198:201], v[110:113]
	v_mfma_f32_16x16x32_bf16 v[102:105], v[180:183], v[198:201], v[102:105]
	v_mfma_f32_16x16x32_bf16 v[76:79], v[172:175], v[206:209], v[76:79]
	v_mfma_f32_16x16x32_bf16 v[68:71], v[180:183], v[206:209], v[68:71]
	v_mfma_f32_16x16x32_bf16 v[44:47], v[172:175], v[214:217], v[44:47]
	v_mfma_f32_16x16x32_bf16 v[36:39], v[180:183], v[214:217], v[36:39]
	v_mfma_f32_16x16x32_bf16 v[12:15], v[172:175], v[222:225], v[12:15]
	v_mfma_f32_16x16x32_bf16 v[4:7], v[180:183], v[222:225], v[4:7]
	s_setprio 0
	s_barrier
	s_add_i32 s40, s40, s50
	s_mov_b32 m0, s40
	ds_read_b128 v[194:197], v148 offset:49152
	ds_read_b128 v[198:201], v148 offset:50176
	ds_read_b128 v[202:205], v148 offset:51200
	ds_read_b128 v[206:209], v148 offset:52224
	ds_read_b128 v[210:213], v148 offset:53248
	ds_read_b128 v[214:217], v148 offset:54272
	ds_read_b128 v[218:221], v148 offset:55296
	ds_read_b128 v[222:225], v148 offset:56320
	global_load_lds_dwordx4 v192, s[78:79]
	s_add_i32 m0, s40, 0x2000
	s_add_i32 s40, s50, 0x1c010
	global_load_lds_dwordx4 v193, s[78:79]
	s_mov_b32 m0, s40
	s_nop 0
	global_load_lds_dwordx4 v226, s[78:79]
	s_add_i32 m0, s40, 0x2000
	s_nop 0
	global_load_lds_dwordx4 v227, s[78:79]
	s_mov_b32 m0, s85
	s_nop 0
	global_load_lds_dwordx4 v228, s[48:49]
	s_mov_b32 m0, s86
	s_nop 0
	global_load_lds_dwordx4 v229, s[48:49]
	s_waitcnt vmcnt(8)
	s_waitcnt lgkmcnt(0)
	s_barrier
	s_setprio 1
	s_waitcnt lgkmcnt(0)
	v_mfma_f32_16x16x32_bf16 v[126:129], v[130:133], v[194:197], v[126:129]
	v_mfma_f32_16x16x32_bf16 v[114:117], v[138:141], v[194:197], v[114:117]
	v_mfma_f32_16x16x32_bf16 v[88:91], v[130:133], v[202:205], v[88:91]
	v_mfma_f32_16x16x32_bf16 v[80:83], v[138:141], v[202:205], v[80:83]
	v_mfma_f32_16x16x32_bf16 v[56:59], v[130:133], v[210:213], v[56:59]
	v_mfma_f32_16x16x32_bf16 v[48:51], v[138:141], v[210:213], v[48:51]
	v_mfma_f32_16x16x32_bf16 v[24:27], v[130:133], v[218:221], v[24:27]
	v_mfma_f32_16x16x32_bf16 v[16:19], v[138:141], v[218:221], v[16:19]
	v_mfma_f32_16x16x32_bf16 v[126:129], v[134:137], v[198:201], v[126:129]
	v_mfma_f32_16x16x32_bf16 v[114:117], v[142:145], v[198:201], v[114:117]
	v_mfma_f32_16x16x32_bf16 v[88:91], v[134:137], v[206:209], v[88:91]
	v_mfma_f32_16x16x32_bf16 v[80:83], v[142:145], v[206:209], v[80:83]
	v_mfma_f32_16x16x32_bf16 v[56:59], v[134:137], v[214:217], v[56:59]
	v_mfma_f32_16x16x32_bf16 v[48:51], v[142:145], v[214:217], v[48:51]
	v_mfma_f32_16x16x32_bf16 v[24:27], v[134:137], v[222:225], v[24:27]
	v_mfma_f32_16x16x32_bf16 v[16:19], v[142:145], v[222:225], v[16:19]
	s_setprio 0
	s_setprio 1
	v_mfma_f32_16x16x32_bf16 v[106:109], v[168:171], v[194:197], v[106:109]
	v_mfma_f32_16x16x32_bf16 v[98:101], v[176:179], v[194:197], v[98:101]
	v_mfma_f32_16x16x32_bf16 v[72:75], v[168:171], v[202:205], v[72:75]
	v_mfma_f32_16x16x32_bf16 v[64:67], v[176:179], v[202:205], v[64:67]
	v_mfma_f32_16x16x32_bf16 v[40:43], v[168:171], v[210:213], v[40:43]
	v_mfma_f32_16x16x32_bf16 v[32:35], v[176:179], v[210:213], v[32:35]
	v_mfma_f32_16x16x32_bf16 v[8:11], v[168:171], v[218:221], v[8:11]
	v_mfma_f32_16x16x32_bf16 v[0:3], v[176:179], v[218:221], v[0:3]
	v_mfma_f32_16x16x32_bf16 v[106:109], v[172:175], v[198:201], v[106:109]
	v_mfma_f32_16x16x32_bf16 v[98:101], v[180:183], v[198:201], v[98:101]
	v_mfma_f32_16x16x32_bf16 v[72:75], v[172:175], v[206:209], v[72:75]
	v_mfma_f32_16x16x32_bf16 v[64:67], v[180:183], v[206:209], v[64:67]
	v_mfma_f32_16x16x32_bf16 v[40:43], v[172:175], v[214:217], v[40:43]
	v_mfma_f32_16x16x32_bf16 v[32:35], v[180:183], v[214:217], v[32:35]
	v_mfma_f32_16x16x32_bf16 v[8:11], v[172:175], v[222:225], v[8:11]
	v_mfma_f32_16x16x32_bf16 v[0:3], v[180:183], v[222:225], v[0:3]
	s_setprio 0
	s_barrier
	s_add_u32 s80, s80, 0x100
	s_addc_u32 s81, s81, 0
	s_add_u32 s24, s24, 0x100
	s_addc_u32 s25, s25, 0
	s_cmp_ge_i32 vcc_lo, s4
	s_mov_b32 s48, vcc_lo
	s_cbranch_scc0 .LBB0_384
	s_add_i32 s78, 16, 0x1c000
	s_movk_i32 s80, 0x4000
	v_add_u32_e32 v192, 64, v191

; template <class Epi, class Sched, bool ALIGN_EPI = false, bool SP2 = false>
; __device__ __forceinline__ void gemm_phase(PG8_LAS unsigned char* lds, const Gemm g, const Sched& S, const Epi& E, int wid_s_) {
;     ...
;     f32x4 acc[2][2][4][2];
; #pragma unroll
;     for (int a = 0; a < 2; ++a)
; #pragma unroll
;         for (int b = 0; b < 2; ++b)
; #pragma unroll
;             for (int m = 0; m < 4; ++m)
; #pragma unroll
;                 for (int n = 0; n < 2; ++n) acc[a][b][m][n] = (f32x4){0.f, 0.f, 0.f, 0.f};
;     ...
; #pragma unroll
;         for (int a = 0; a < 2; ++a)
; #pragma unroll
;             for (int b = 0; b < 2; ++b)
; #pragma unroll
;                 for (int m = 0; m < 4; ++m)
; #pragma unroll
;                     for (int n = 0; n < 2; ++n) acc[a][b][m][n] = (f32x4){0.f, 0.f, 0.f, 0.f};
;         cur = nxt; cA = nA; cB = nB; ++ui;
.LBB0_786:
	v_mov_b32_e32 v129, 0
	s_andn2_b64 vcc, exec, s[12:13]
	v_mov_b32_e32 v128, 0
	v_mov_b32_e32 v127, 0
	v_mov_b32_e32 v126, 0
	v_mov_b32_e32 v125, 0
	v_mov_b32_e32 v124, 0
	v_mov_b32_e32 v123, 0
	v_mov_b32_e32 v122, 0
	v_mov_b32_e32 v103, 0
	v_mov_b32_e32 v102, 0
	v_mov_b32_e32 v105, 0
	v_mov_b32_e32 v104, 0
	v_mov_b32_e32 v111, 0
	v_mov_b32_e32 v110, 0
	v_mov_b32_e32 v113, 0
	v_mov_b32_e32 v112, 0
	v_mov_b32_e32 v85, 0
	v_mov_b32_e32 v84, 0
	v_mov_b32_e32 v87, 0
	v_mov_b32_e32 v86, 0
	v_mov_b32_e32 v93, 0
	v_mov_b32_e32 v92, 0
	v_mov_b32_e32 v95, 0
	v_mov_b32_e32 v94, 0
	v_mov_b32_e32 v73, 0
	v_mov_b32_e32 v72, 0
	v_mov_b32_e32 v75, 0
	v_mov_b32_e32 v74, 0
	v_mov_b32_e32 v77, 0
	v_mov_b32_e32 v76, 0
	v_mov_b32_e32 v79, 0
	v_mov_b32_e32 v78, 0
	v_mov_b32_e32 v143, 0
	v_mov_b32_e32 v142, 0
	v_mov_b32_e32 v145, 0
	v_mov_b32_e32 v144, 0
	v_mov_b32_e32 v153, 0
	v_mov_b32_e32 v152, 0
	v_mov_b32_e32 v155, 0
	v_mov_b32_e32 v154, 0
	v_mov_b32_e32 v115, 0
	v_mov_b32_e32 v114, 0
	v_mov_b32_e32 v117, 0
	v_mov_b32_e32 v116, 0
	v_mov_b32_e32 v119, 0
	v_mov_b32_e32 v118, 0
	v_mov_b32_e32 v121, 0
	v_mov_b32_e32 v120, 0
	v_mov_b32_e32 v99, 0
	v_mov_b32_e32 v98, 0
	v_mov_b32_e32 v101, 0
	v_mov_b32_e32 v100, 0
	v_mov_b32_e32 v107, 0
	v_mov_b32_e32 v106, 0
	v_mov_b32_e32 v109, 0
	v_mov_b32_e32 v108, 0
	v_mov_b32_e32 v71, 0
	v_mov_b32_e32 v70, 0
	v_mov_b32_e32 v69, 0
	v_mov_b32_e32 v68, 0
	v_mov_b32_e32 v67, 0
	v_mov_b32_e32 v66, 0
	v_mov_b32_e32 v65, 0
	v_mov_b32_e32 v64, 0
	v_mov_b32_e32 v63, 0
	v_mov_b32_e32 v62, 0
	v_mov_b32_e32 v61, 0
	v_mov_b32_e32 v60, 0
	v_mov_b32_e32 v59, 0
	v_mov_b32_e32 v58, 0
	v_mov_b32_e32 v57, 0
	v_mov_b32_e32 v56, 0
	v_mov_b32_e32 v37, 0
	v_mov_b32_e32 v36, 0
	v_mov_b32_e32 v39, 0
	v_mov_b32_e32 v38, 0
	v_mov_b32_e32 v45, 0
	v_mov_b32_e32 v44, 0
	v_mov_b32_e32 v47, 0
	v_mov_b32_e32 v46, 0
	v_mov_b32_e32 v21, 0
	v_mov_b32_e32 v20, 0
	v_mov_b32_e32 v23, 0
	v_mov_b32_e32 v22, 0
	v_mov_b32_e32 v29, 0
	v_mov_b32_e32 v28, 0
	v_mov_b32_e32 v31, 0
	v_mov_b32_e32 v30, 0
	v_mov_b32_e32 v9, 0
	v_mov_b32_e32 v8, 0
	v_mov_b32_e32 v11, 0
	v_mov_b32_e32 v10, 0
	v_mov_b32_e32 v13, 0
	v_mov_b32_e32 v12, 0
	v_mov_b32_e32 v15, 0
	v_mov_b32_e32 v14, 0
	v_mov_b32_e32 v81, 0
	v_mov_b32_e32 v80, 0
	v_mov_b32_e32 v83, 0
	v_mov_b32_e32 v82, 0
	v_mov_b32_e32 v89, 0
	v_mov_b32_e32 v88, 0
	v_mov_b32_e32 v91, 0
	v_mov_b32_e32 v90, 0
	v_mov_b32_e32 v49, 0
	v_mov_b32_e32 v48, 0
	v_mov_b32_e32 v51, 0
	v_mov_b32_e32 v50, 0
	v_mov_b32_e32 v53, 0
	v_mov_b32_e32 v52, 0
	v_mov_b32_e32 v55, 0
	v_mov_b32_e32 v54, 0
	v_mov_b32_e32 v33, 0
	v_mov_b32_e32 v32, 0
	v_mov_b32_e32 v35, 0
	v_mov_b32_e32 v34, 0
	v_mov_b32_e32 v41, 0
	v_mov_b32_e32 v40, 0
	v_mov_b32_e32 v43, 0
	v_mov_b32_e32 v42, 0
	v_mov_b32_e32 v7, 0
	v_mov_b32_e32 v6, 0
	v_mov_b32_e32 v5, 0
	v_mov_b32_e32 v4, 0
	v_mov_b32_e32 v3, 0
	v_mov_b32_e32 v2, 0
	v_mov_b32_e32 v1, 0
	v_mov_b32_e32 v0, 0
	s_cbranch_vccnz .LBB0_790
	s_add_u32 s91, s18, 0x100
	s_addc_u32 vcc_lo, s19, 0
	s_add_u32 s18, s20, 0x80
	v_mov_b32_e32 v0, 0
	s_addc_u32 s19, s21, 0
	s_mov_b32 s20, 0
	v_mov_b32_e32 v1, v0
	v_mov_b32_e32 v2, v0
	v_mov_b32_e32 v3, v0
	v_mov_b32_e32 v4, v0
	v_mov_b32_e32 v5, v0
	v_mov_b32_e32 v6, v0
	v_mov_b32_e32 v7, v0
	v_mov_b32_e32 v8, v0
	v_mov_b32_e32 v9, v0
	v_mov_b32_e32 v10, v0
	v_mov_b32_e32 v11, v0
	v_mov_b32_e32 v12, v0
	v_mov_b32_e32 v13, v0
	v_mov_b32_e32 v14, v0
	v_mov_b32_e32 v15, v0
	v_mov_b32_e32 v20, v0
	v_mov_b32_e32 v21, v0
	v_mov_b32_e32 v22, v0
	v_mov_b32_e32 v23, v0
	v_mov_b32_e32 v28, v0
	v_mov_b32_e32 v29, v0
	v_mov_b32_e32 v30, v0
	v_mov_b32_e32 v31, v0
	v_mov_b32_e32 v36, v0
	v_mov_b32_e32 v37, v0
	v_mov_b32_e32 v38, v0
	v_mov_b32_e32 v39, v0
	v_mov_b32_e32 v44, v0
	v_mov_b32_e32 v45, v0
	v_mov_b32_e32 v46, v0
	v_mov_b32_e32 v47, v0
	v_mov_b32_e32 v16, v0
	v_mov_b32_e32 v17, v0
	v_mov_b32_e32 v18, v0
	v_mov_b32_e32 v19, v0
	v_mov_b32_e32 v24, v0
	v_mov_b32_e32 v25, v0
	v_mov_b32_e32 v26, v0
	v_mov_b32_e32 v27, v0
	v_mov_b32_e32 v32, v0
	v_mov_b32_e32 v33, v0
	v_mov_b32_e32 v34, v0
	v_mov_b32_e32 v35, v0
	v_mov_b32_e32 v40, v0
	v_mov_b32_e32 v41, v0
	v_mov_b32_e32 v42, v0
	v_mov_b32_e32 v43, v0
	v_mov_b32_e32 v48, v0
	v_mov_b32_e32 v49, v0
	v_mov_b32_e32 v50, v0
	v_mov_b32_e32 v51, v0
	v_mov_b32_e32 v52, v0
	v_mov_b32_e32 v53, v0
	v_mov_b32_e32 v54, v0
	v_mov_b32_e32 v55, v0
	v_mov_b32_e32 v56, v0
	v_mov_b32_e32 v57, v0
	v_mov_b32_e32 v58, v0
	v_mov_b32_e32 v59, v0
	v_mov_b32_e32 v60, v0
	v_mov_b32_e32 v61, v0
	v_mov_b32_e32 v62, v0
	v_mov_b32_e32 v63, v0
	v_mov_b32_e32 v64, v0
	v_mov_b32_e32 v65, v0
	v_mov_b32_e32 v66, v0
	v_mov_b32_e32 v67, v0
	v_mov_b32_e32 v68, v0
	v_mov_b32_e32 v69, v0
	v_mov_b32_e32 v70, v0
	v_mov_b32_e32 v71, v0
	v_mov_b32_e32 v72, v0
	v_mov_b32_e32 v73, v0
	v_mov_b32_e32 v74, v0
	v_mov_b32_e32 v75, v0
	v_mov_b32_e32 v76, v0
	v_mov_b32_e32 v77, v0
	v_mov_b32_e32 v78, v0
	v_mov_b32_e32 v79, v0
	v_mov_b32_e32 v84, v0
	v_mov_b32_e32 v85, v0
	v_mov_b32_e32 v86, v0
	v_mov_b32_e32 v87, v0
	v_mov_b32_e32 v92, v0
	v_mov_b32_e32 v93, v0
	v_mov_b32_e32 v94, v0
	v_mov_b32_e32 v95, v0
	v_mov_b32_e32 v102, v0
	v_mov_b32_e32 v103, v0
	v_mov_b32_e32 v104, v0
	v_mov_b32_e32 v105, v0
	v_mov_b32_e32 v110, v0
	v_mov_b32_e32 v111, v0
	v_mov_b32_e32 v112, v0
	v_mov_b32_e32 v113, v0
	v_mov_b32_e32 v80, v0
	v_mov_b32_e32 v81, v0
	v_mov_b32_e32 v82, v0
	v_mov_b32_e32 v83, v0
	v_mov_b32_e32 v88, v0
	v_mov_b32_e32 v89, v0
	v_mov_b32_e32 v90, v0
	v_mov_b32_e32 v91, v0
	v_mov_b32_e32 v98, v0
	v_mov_b32_e32 v99, v0
	v_mov_b32_e32 v100, v0
	v_mov_b32_e32 v101, v0
	v_mov_b32_e32 v106, v0
	v_mov_b32_e32 v107, v0
	v_mov_b32_e32 v108, v0
	v_mov_b32_e32 v109, v0
	v_mov_b32_e32 v114, v0
	v_mov_b32_e32 v115, v0
	v_mov_b32_e32 v116, v0
	v_mov_b32_e32 v117, v0
	v_mov_b32_e32 v118, v0
	v_mov_b32_e32 v119, v0
	v_mov_b32_e32 v120, v0
	v_mov_b32_e32 v121, v0
	v_mov_b32_e32 v122, v0
	v_mov_b32_e32 v123, v0
	v_mov_b32_e32 v124, v0
	v_mov_b32_e32 v125, v0
	v_mov_b32_e32 v126, v0
	v_mov_b32_e32 v127, v0
	v_mov_b32_e32 v128, v0
	v_mov_b32_e32 v129, v0
	v_add_u32_e32 v178, s4, v132
	v_add_u32_e32 v179, s4, v136
	v_add_u32_e32 v188, s4, v130
	v_add_u32_e32 v189, s4, v134
	v_add_u32_e32 v194, s42, v132
	v_add_u32_e32 v195, s42, v136
	v_add_u32_e32 v226, s42, v130
	v_add_u32_e32 v227, s42, v134
	v_add_u32_e32 v224, s42, v178
	v_add_u32_e32 v225, s42, v179
; #define PG8_STAGE(bufoff, gbase, voff) do { _Pragma("unroll") for (int _i = 0; _i < 2; ++_i) \
;         __builtin_amdgcn_global_load_lds((const unsigned*)((const char*)(gbase) + (voff)[_i]), (PG8_LAS unsigned*)(lds + (bufoff) + ldsw + _i * 8192), 16, 0, 0); } while (0)
; #define PG8_LDA(dst, b, h) do { _Pragma("unroll") for (int m = 0; m < 4; ++m) _Pragma("unroll") for (int k = 0; k < 2; ++k) dst[m][k] = *(const PG8_LAS bf16x8*)(lds + PG8_SA(b, h) + aoff + m * 2048 + k * 1024); } while (0)
; #define PG8_LDB(dst, b, h) do { _Pragma("unroll") for (int n = 0; n < 2; ++n) _Pragma("unroll") for (int k = 0; k < 2; ++k) dst[n][k] = *(const PG8_LAS bf16x8*)(lds + PG8_SB(b, h) + boff + n * 2048 + k * 1024); } while (0)
; #define PG8_MMA(ai, bj, At, Bt) do { __builtin_amdgcn_s_setprio(1); _Pragma("unroll") for (int m = 0; m < 4; ++m) _Pragma("unroll") for (int n = 0; n < 2; ++n) _Pragma("unroll") for (int k = 0; k < 2; ++k) \
;         acc[ai][bj][m][n] = __builtin_amdgcn_mfma_f32_16x16x32_bf16(Bt[n][k], At[m][k], acc[ai][bj][m][n], 0, 0, 0); __builtin_amdgcn_s_setprio(0); } while (0)
; #define PG8_WAIT_V(n) asm volatile("s_waitcnt vmcnt(" #n ")" ::: "memory")
; #define PG8_WAIT_L(n) asm volatile("s_waitcnt lgkmcnt(" #n ")" ::: "memory")
; #define PG8_BAR __builtin_amdgcn_s_barrier()
; #define PG8_SCHED __builtin_amdgcn_sched_barrier(0)
; template <class Epi, class Sched, bool ALIGN_EPI = false, bool SP2 = false>
; __device__ __forceinline__ void gemm_phase(PG8_LAS unsigned char* lds, const Gemm g, const Sched& S, const Epi& E, int wid_s_) {
;     ...
;             PG8_LDB(B0, 0, 0); PG8_LDB(B1, 0, 1); PG8_SCHED; PG8_LDA(At, 0, 0); PG8_STAGE(PG8_SA(1, 1), a1 + hstep, voffA);
;             PG8_WAIT_V(8); PG8_WAIT_L(0); PG8_BAR; PG8_MMA(0, 0, At, B0); PG8_MMA(0, 1, At, B1); PG8_BAR; PG8_SCHED;
;             PG8_LDA(At, 0, 1); PG8_STAGE(PG8_SB(0, 0), b2, voffB); PG8_STAGE(PG8_SB(0, 1), b2 + hstep, voffB); PG8_STAGE(PG8_SA(0, 0), a2, voffA);
;             PG8_WAIT_V(8); PG8_WAIT_L(0); PG8_BAR; PG8_MMA(1, 0, At, B0); PG8_MMA(1, 1, At, B1); PG8_BAR; PG8_SCHED;
.LBB0_788:
	s_add_i32 vcc_hi, s20, 2
	s_add_u32 s8, s18, 0x80
	s_addc_u32 s9, s19, 0
	s_add_i32 s78, 16, 0x10000
	s_cmp_eq_u32 s85, s20
	s_cselect_b32 s21, s3, s9
	s_cselect_b32 s20, s2, s8
	v_add_u32_e32 v96, s78, v147
	s_cselect_b32 s9, s17, vcc_lo
	s_cselect_b32 s8, s16, s91
	s_add_i32 s79, 16, 0x14000
	ds_read_b128 v[142:145], v96
	ds_read_b128 v[150:153], v96 offset:1024
	ds_read_b128 v[154:157], v96 offset:2048
	ds_read_b128 v[158:161], v96 offset:3072
	v_add_u32_e32 v96, s79, v147
	ds_read_b128 v[162:165], v96
	ds_read_b128 v[166:169], v96 offset:1024
	ds_read_b128 v[170:173], v96 offset:2048
	ds_read_b128 v[174:177], v96 offset:3072
	s_add_i32 m0, s48, 0xc000
	ds_read_b128 v[180:183], v149
	ds_read_b128 v[196:199], v149 offset:1024
	ds_read_b128 v[200:203], v149 offset:2048
	ds_read_b128 v[204:207], v149 offset:3072
	ds_read_b128 v[208:211], v149 offset:4096
	ds_read_b128 v[212:215], v149 offset:5120
	ds_read_b128 v[216:219], v149 offset:6144
	ds_read_b128 v[220:223], v149 offset:7168
	global_load_lds_dwordx4 v140, s[18:19]
	s_add_i32 m0, s48, 0xe000
	s_nop 0
	global_load_lds_dwordx4 v138, s[18:19]
	s_waitcnt vmcnt(8)
	s_waitcnt lgkmcnt(0)
	s_barrier
	s_setprio 1
	s_waitcnt lgkmcnt(0)
	v_mfma_f32_16x16x32_bf16 v[126:129], v[142:145], v[180:183], v[126:129]
	v_mfma_f32_16x16x32_bf16 v[122:125], v[154:157], v[180:183], v[122:125]
	v_mfma_f32_16x16x32_bf16 v[118:121], v[142:145], v[200:203], v[118:121]
	v_mfma_f32_16x16x32_bf16 v[114:117], v[154:157], v[200:203], v[114:117]
	v_mfma_f32_16x16x32_bf16 v[106:109], v[142:145], v[208:211], v[106:109]
	v_mfma_f32_16x16x32_bf16 v[98:101], v[154:157], v[208:211], v[98:101]
	v_mfma_f32_16x16x32_bf16 v[88:91], v[142:145], v[216:219], v[88:91]
	v_mfma_f32_16x16x32_bf16 v[80:83], v[154:157], v[216:219], v[80:83]
	v_mfma_f32_16x16x32_bf16 v[126:129], v[150:153], v[196:199], v[126:129]
	v_mfma_f32_16x16x32_bf16 v[122:125], v[158:161], v[196:199], v[122:125]
	v_mfma_f32_16x16x32_bf16 v[118:121], v[150:153], v[204:207], v[118:121]
	v_mfma_f32_16x16x32_bf16 v[114:117], v[158:161], v[204:207], v[114:117]
	v_mfma_f32_16x16x32_bf16 v[106:109], v[150:153], v[212:215], v[106:109]
	v_mfma_f32_16x16x32_bf16 v[98:101], v[158:161], v[212:215], v[98:101]
	v_mfma_f32_16x16x32_bf16 v[88:91], v[150:153], v[220:223], v[88:91]
	v_mfma_f32_16x16x32_bf16 v[80:83], v[158:161], v[220:223], v[80:83]
	s_setprio 0
	s_setprio 1
	v_mfma_f32_16x16x32_bf16 v[110:113], v[162:165], v[180:183], v[110:113]
	v_mfma_f32_16x16x32_bf16 v[102:105], v[170:173], v[180:183], v[102:105]
	v_mfma_f32_16x16x32_bf16 v[92:95], v[162:165], v[200:203], v[92:95]
	v_mfma_f32_16x16x32_bf16 v[84:87], v[170:173], v[200:203], v[84:87]
	v_mfma_f32_16x16x32_bf16 v[76:79], v[162:165], v[208:211], v[76:79]
	v_mfma_f32_16x16x32_bf16 v[72:75], v[170:173], v[208:211], v[72:75]
	v_mfma_f32_16x16x32_bf16 v[68:71], v[162:165], v[216:219], v[68:71]
	v_mfma_f32_16x16x32_bf16 v[64:67], v[170:173], v[216:219], v[64:67]
	v_mfma_f32_16x16x32_bf16 v[110:113], v[166:169], v[196:199], v[110:113]
	v_mfma_f32_16x16x32_bf16 v[102:105], v[174:177], v[196:199], v[102:105]
	v_mfma_f32_16x16x32_bf16 v[92:95], v[166:169], v[204:207], v[92:95]
	v_mfma_f32_16x16x32_bf16 v[84:87], v[174:177], v[204:207], v[84:87]
	v_mfma_f32_16x16x32_bf16 v[76:79], v[166:169], v[212:215], v[76:79]
	v_mfma_f32_16x16x32_bf16 v[72:75], v[174:177], v[212:215], v[72:75]
	v_mfma_f32_16x16x32_bf16 v[68:71], v[166:169], v[220:223], v[68:71]
	v_mfma_f32_16x16x32_bf16 v[64:67], v[174:177], v[220:223], v[64:67]
	s_setprio 0
	s_barrier
	s_add_i32 s78, s78, s41
	s_mov_b32 m0, s78
	ds_read_b128 v[180:183], v149 offset:16384
	ds_read_b128 v[196:199], v149 offset:17408
	ds_read_b128 v[200:203], v149 offset:18432
	ds_read_b128 v[204:207], v149 offset:19456
	ds_read_b128 v[208:211], v149 offset:20480
	ds_read_b128 v[212:215], v149 offset:21504
	ds_read_b128 v[216:219], v149 offset:22528
	ds_read_b128 v[220:223], v149 offset:23552
	global_load_lds_dwordx4 v132, s[8:9]
	s_add_i32 m0, s78, 0x2000
	s_add_i32 s78, s79, s41
	global_load_lds_dwordx4 v136, s[8:9]
	s_mov_b32 m0, s78
	s_nop 0
	global_load_lds_dwordx4 v178, s[8:9]
	s_add_i32 m0, s78, 0x2000
	s_nop 0
	global_load_lds_dwordx4 v179, s[8:9]
	s_mov_b32 m0, s48
	s_nop 0
	global_load_lds_dwordx4 v130, s[20:21]
	s_mov_b32 m0, s49
	s_nop 0
	global_load_lds_dwordx4 v134, s[20:21]
	s_waitcnt vmcnt(8)
	s_waitcnt lgkmcnt(0)
	s_barrier
	s_setprio 1
	s_waitcnt lgkmcnt(0)
	v_mfma_f32_16x16x32_bf16 v[60:63], v[142:145], v[180:183], v[60:63]
	v_mfma_f32_16x16x32_bf16 v[56:59], v[154:157], v[180:183], v[56:59]
	v_mfma_f32_16x16x32_bf16 v[52:55], v[142:145], v[200:203], v[52:55]
	v_mfma_f32_16x16x32_bf16 v[48:51], v[154:157], v[200:203], v[48:51]
	v_mfma_f32_16x16x32_bf16 v[40:43], v[142:145], v[208:211], v[40:43]
	v_mfma_f32_16x16x32_bf16 v[32:35], v[154:157], v[208:211], v[32:35]
	v_mfma_f32_16x16x32_bf16 v[24:27], v[142:145], v[216:219], v[24:27]
	v_mfma_f32_16x16x32_bf16 v[16:19], v[154:157], v[216:219], v[16:19]
	v_mfma_f32_16x16x32_bf16 v[60:63], v[150:153], v[196:199], v[60:63]
	v_mfma_f32_16x16x32_bf16 v[56:59], v[158:161], v[196:199], v[56:59]
	v_mfma_f32_16x16x32_bf16 v[52:55], v[150:153], v[204:207], v[52:55]
	v_mfma_f32_16x16x32_bf16 v[48:51], v[158:161], v[204:207], v[48:51]
	v_mfma_f32_16x16x32_bf16 v[40:43], v[150:153], v[212:215], v[40:43]
	v_mfma_f32_16x16x32_bf16 v[32:35], v[158:161], v[212:215], v[32:35]
	v_mfma_f32_16x16x32_bf16 v[24:27], v[150:153], v[220:223], v[24:27]
	v_mfma_f32_16x16x32_bf16 v[16:19], v[158:161], v[220:223], v[16:19]
	s_setprio 0
	s_setprio 1
	v_mfma_f32_16x16x32_bf16 v[44:47], v[162:165], v[180:183], v[44:47]
	v_mfma_f32_16x16x32_bf16 v[36:39], v[170:173], v[180:183], v[36:39]
	v_mfma_f32_16x16x32_bf16 v[28:31], v[162:165], v[200:203], v[28:31]
	v_mfma_f32_16x16x32_bf16 v[20:23], v[170:173], v[200:203], v[20:23]
	v_mfma_f32_16x16x32_bf16 v[12:15], v[162:165], v[208:211], v[12:15]
	v_mfma_f32_16x16x32_bf16 v[8:11], v[170:173], v[208:211], v[8:11]
	v_mfma_f32_16x16x32_bf16 v[4:7], v[162:165], v[216:219], v[4:7]
	v_mfma_f32_16x16x32_bf16 v[0:3], v[170:173], v[216:219], v[0:3]
	v_mfma_f32_16x16x32_bf16 v[44:47], v[166:169], v[196:199], v[44:47]
	v_mfma_f32_16x16x32_bf16 v[36:39], v[174:177], v[196:199], v[36:39]
	v_mfma_f32_16x16x32_bf16 v[28:31], v[166:169], v[204:207], v[28:31]
	v_mfma_f32_16x16x32_bf16 v[20:23], v[174:177], v[204:207], v[20:23]
	v_mfma_f32_16x16x32_bf16 v[12:15], v[166:169], v[212:215], v[12:15]
	v_mfma_f32_16x16x32_bf16 v[8:11], v[174:177], v[212:215], v[8:11]
	v_mfma_f32_16x16x32_bf16 v[4:7], v[166:169], v[220:223], v[4:7]
	v_mfma_f32_16x16x32_bf16 v[0:3], v[174:177], v[220:223], v[0:3]
	s_setprio 0
	s_barrier
; #define PG8_STAGE(bufoff, gbase, voff) do { _Pragma("unroll") for (int _i = 0; _i < 2; ++_i) \
;         __builtin_amdgcn_global_load_lds((const unsigned*)((const char*)(gbase) + (voff)[_i]), (PG8_LAS unsigned*)(lds + (bufoff) + ldsw + _i * 8192), 16, 0, 0); } while (0)
; #define PG8_LDA(dst, b, h) do { _Pragma("unroll") for (int m = 0; m < 4; ++m) _Pragma("unroll") for (int k = 0; k < 2; ++k) dst[m][k] = *(const PG8_LAS bf16x8*)(lds + PG8_SA(b, h) + aoff + m * 2048 + k * 1024); } while (0)
; #define PG8_LDB(dst, b, h) do { _Pragma("unroll") for (int n = 0; n < 2; ++n) _Pragma("unroll") for (int k = 0; k < 2; ++k) dst[n][k] = *(const PG8_LAS bf16x8*)(lds + PG8_SB(b, h) + boff + n * 2048 + k * 1024); } while (0)
; #define PG8_MMA(ai, bj, At, Bt) do { __builtin_amdgcn_s_setprio(1); _Pragma("unroll") for (int m = 0; m < 4; ++m) _Pragma("unroll") for (int n = 0; n < 2; ++n) _Pragma("unroll") for (int k = 0; k < 2; ++k) \
;         acc[ai][bj][m][n] = __builtin_amdgcn_mfma_f32_16x16x32_bf16(Bt[n][k], At[m][k], acc[ai][bj][m][n], 0, 0, 0); __builtin_amdgcn_s_setprio(0); } while (0)
; #define PG8_WAIT_V(n) asm volatile("s_waitcnt vmcnt(" #n ")" ::: "memory")
; #define PG8_WAIT_L(n) asm volatile("s_waitcnt lgkmcnt(" #n ")" ::: "memory")
; #define PG8_BAR __builtin_amdgcn_s_barrier()
; #define PG8_SCHED __builtin_amdgcn_sched_barrier(0)
; template <class Epi, class Sched, bool ALIGN_EPI = false, bool SP2 = false>
; __device__ __forceinline__ void gemm_phase(PG8_LAS unsigned char* lds, const Gemm g, const Sched& S, const Epi& E, int wid_s_) {
;     ...
;             PG8_LDB(B0, 1, 0); PG8_LDB(B1, 1, 1); PG8_SCHED; PG8_LDA(At, 1, 0); PG8_STAGE(PG8_SA(0, 1), a2 + hstep, voffA);
;             PG8_WAIT_V(8); PG8_WAIT_L(0); PG8_BAR; PG8_MMA(0, 0, At, B0); PG8_MMA(0, 1, At, B1); PG8_BAR; PG8_SCHED;
;             PG8_LDA(At, 1, 1); PG8_STAGE(PG8_SB(1, 0), b3, voffB); PG8_STAGE(PG8_SB(1, 1), b3 + hstep, voffB); PG8_STAGE(PG8_SA(1, 0), a3, voffA);
;             PG8_WAIT_V(8); PG8_WAIT_L(0); PG8_BAR; PG8_MMA(1, 0, At, B0); PG8_MMA(1, 1, At, B1); PG8_BAR; PG8_SCHED;
	s_add_i32 s78, 16, 0x18000
	v_add_u32_e32 v96, s78, v147
	s_add_i32 s79, 16, 0x1c000
	ds_read_b128 v[142:145], v96
	ds_read_b128 v[150:153], v96 offset:1024
	ds_read_b128 v[154:157], v96 offset:2048
	ds_read_b128 v[158:161], v96 offset:3072
	v_add_u32_e32 v96, s79, v147
	ds_read_b128 v[162:165], v96
	ds_read_b128 v[166:169], v96 offset:1024
	ds_read_b128 v[170:173], v96 offset:2048
	ds_read_b128 v[174:177], v96 offset:3072
	s_mov_b32 m0, s50
	ds_read_b128 v[180:183], v149 offset:32768
	ds_read_b128 v[196:199], v149 offset:33792
	ds_read_b128 v[200:203], v149 offset:34816
	ds_read_b128 v[204:207], v149 offset:35840
	ds_read_b128 v[208:211], v149 offset:36864
	ds_read_b128 v[212:215], v149 offset:37888
	ds_read_b128 v[216:219], v149 offset:38912
	ds_read_b128 v[220:223], v149 offset:39936
	global_load_lds_dwordx4 v188, s[20:21]
	s_mov_b32 m0, s51
	s_nop 0
	global_load_lds_dwordx4 v189, s[20:21]
	s_waitcnt vmcnt(8)
	s_waitcnt lgkmcnt(0)
	s_barrier
	s_setprio 1
	s_waitcnt lgkmcnt(0)
	v_mfma_f32_16x16x32_bf16 v[126:129], v[142:145], v[180:183], v[126:129]
	v_mfma_f32_16x16x32_bf16 v[122:125], v[154:157], v[180:183], v[122:125]
	v_mfma_f32_16x16x32_bf16 v[118:121], v[142:145], v[200:203], v[118:121]
	v_mfma_f32_16x16x32_bf16 v[114:117], v[154:157], v[200:203], v[114:117]
	v_mfma_f32_16x16x32_bf16 v[106:109], v[142:145], v[208:211], v[106:109]
	v_mfma_f32_16x16x32_bf16 v[98:101], v[154:157], v[208:211], v[98:101]
	v_mfma_f32_16x16x32_bf16 v[88:91], v[142:145], v[216:219], v[88:91]
	v_mfma_f32_16x16x32_bf16 v[80:83], v[154:157], v[216:219], v[80:83]
	v_mfma_f32_16x16x32_bf16 v[126:129], v[150:153], v[196:199], v[126:129]
	v_mfma_f32_16x16x32_bf16 v[122:125], v[158:161], v[196:199], v[122:125]
	v_mfma_f32_16x16x32_bf16 v[118:121], v[150:153], v[204:207], v[118:121]
	v_mfma_f32_16x16x32_bf16 v[114:117], v[158:161], v[204:207], v[114:117]
	v_mfma_f32_16x16x32_bf16 v[106:109], v[150:153], v[212:215], v[106:109]
	v_mfma_f32_16x16x32_bf16 v[98:101], v[158:161], v[212:215], v[98:101]
	v_mfma_f32_16x16x32_bf16 v[88:91], v[150:153], v[220:223], v[88:91]
	v_mfma_f32_16x16x32_bf16 v[80:83], v[158:161], v[220:223], v[80:83]
	s_setprio 0
	s_setprio 1
	v_mfma_f32_16x16x32_bf16 v[110:113], v[162:165], v[180:183], v[110:113]
	v_mfma_f32_16x16x32_bf16 v[102:105], v[170:173], v[180:183], v[102:105]
	v_mfma_f32_16x16x32_bf16 v[92:95], v[162:165], v[200:203], v[92:95]
	v_mfma_f32_16x16x32_bf16 v[84:87], v[170:173], v[200:203], v[84:87]
	v_mfma_f32_16x16x32_bf16 v[76:79], v[162:165], v[208:211], v[76:79]
	v_mfma_f32_16x16x32_bf16 v[72:75], v[170:173], v[208:211], v[72:75]
	v_mfma_f32_16x16x32_bf16 v[68:71], v[162:165], v[216:219], v[68:71]
	v_mfma_f32_16x16x32_bf16 v[64:67], v[170:173], v[216:219], v[64:67]
	v_mfma_f32_16x16x32_bf16 v[110:113], v[166:169], v[196:199], v[110:113]
	v_mfma_f32_16x16x32_bf16 v[102:105], v[174:177], v[196:199], v[102:105]
	v_mfma_f32_16x16x32_bf16 v[92:95], v[166:169], v[204:207], v[92:95]
	v_mfma_f32_16x16x32_bf16 v[84:87], v[174:177], v[204:207], v[84:87]
	v_mfma_f32_16x16x32_bf16 v[76:79], v[166:169], v[212:215], v[76:79]
	v_mfma_f32_16x16x32_bf16 v[72:75], v[174:177], v[212:215], v[72:75]
	v_mfma_f32_16x16x32_bf16 v[68:71], v[166:169], v[220:223], v[68:71]
	v_mfma_f32_16x16x32_bf16 v[64:67], v[174:177], v[220:223], v[64:67]
	s_setprio 0
	s_barrier
	s_add_i32 m0, s78, s41
	ds_read_b128 v[180:183], v149 offset:49152
	ds_read_b128 v[196:199], v149 offset:50176
	ds_read_b128 v[200:203], v149 offset:51200
	ds_read_b128 v[204:207], v149 offset:52224
	ds_read_b128 v[208:211], v149 offset:53248
	ds_read_b128 v[212:215], v149 offset:54272
	ds_read_b128 v[216:219], v149 offset:55296
	ds_read_b128 v[220:223], v149 offset:56320
	global_load_lds_dwordx4 v194, s[8:9]
	s_add_i32 m0, s78, s41
	s_addk_i32 m0, 0x2000
	s_nop 0
	global_load_lds_dwordx4 v195, s[8:9]
	s_add_i32 m0, s79, s41
	s_nop 0
	global_load_lds_dwordx4 v224, s[8:9]
	s_add_i32 m0, s79, s41
	s_addk_i32 m0, 0x2000
	s_nop 0
	global_load_lds_dwordx4 v225, s[8:9]
	s_mov_b32 m0, s80
	s_nop 0
	global_load_lds_dwordx4 v226, s[20:21]
	s_mov_b32 m0, s81
	s_nop 0
	global_load_lds_dwordx4 v227, s[20:21]
	s_waitcnt vmcnt(8)
	s_waitcnt lgkmcnt(0)
	s_barrier
; #define PG8_MMA(ai, bj, At, Bt) do { __builtin_amdgcn_s_setprio(1); _Pragma("unroll") for (int m = 0; m < 4; ++m) _Pragma("unroll") for (int n = 0; n < 2; ++n) _Pragma("unroll") for (int k = 0; k < 2; ++k) \
;         acc[ai][bj][m][n] = __builtin_amdgcn_mfma_f32_16x16x32_bf16(Bt[n][k], At[m][k], acc[ai][bj][m][n], 0, 0, 0); __builtin_amdgcn_s_setprio(0); } while (0)
; #define PG8_WAIT_V(n) asm volatile("s_waitcnt vmcnt(" #n ")" ::: "memory")
; #define PG8_WAIT_L(n) asm volatile("s_waitcnt lgkmcnt(" #n ")" ::: "memory")
; #define PG8_BAR __builtin_amdgcn_s_barrier()
; #define PG8_SCHED __builtin_amdgcn_sched_barrier(0)
; __device__ __forceinline__ unsigned cvtpk(float lo, float hi) { f32x2_t v = {lo, hi}; bf16x2_t b = __builtin_convertvector(v, bf16x2_t); return __builtin_bit_cast(unsigned, b); }
; template <class Epi, class Sched, bool ALIGN_EPI = false, bool SP2 = false>
; __device__ __forceinline__ void gemm_phase(PG8_LAS unsigned char* lds, const Gemm g, const Sched& S, const Epi& E, int wid_s_) {
;     ...
;             PG8_WAIT_V(8); PG8_WAIT_L(0); PG8_BAR; PG8_MMA(1, 0, At, B0); PG8_MMA(1, 1, At, B1); PG8_BAR; PG8_SCHED;
;     __device__ __forceinline__ void operator()(const f32x4 (&acc)[2][2][4][2], const Unit& u, int wr, int wc, int fr, int fq) const {
;     ...
;                     const f32x4 v0 = acc[ai][bj][m][0] * scale, v1 = acc[ai][bj][m][1] * scale;
;                     u32x4 w; w.x = cvtpk(v0[0], v0[1]); w.y = cvtpk(v0[2], v0[3]); w.z = cvtpk(v1[0], v1[1]); w.w = cvtpk(v1[2], v1[3]);
	s_setprio 1
	s_waitcnt lgkmcnt(0)
	v_mfma_f32_16x16x32_bf16 v[60:63], v[142:145], v[180:183], v[60:63]
	v_mfma_f32_16x16x32_bf16 v[56:59], v[154:157], v[180:183], v[56:59]
	v_mfma_f32_16x16x32_bf16 v[52:55], v[142:145], v[200:203], v[52:55]
	v_mfma_f32_16x16x32_bf16 v[48:51], v[154:157], v[200:203], v[48:51]
	v_mfma_f32_16x16x32_bf16 v[40:43], v[142:145], v[208:211], v[40:43]
	v_mfma_f32_16x16x32_bf16 v[32:35], v[154:157], v[208:211], v[32:35]
	v_mfma_f32_16x16x32_bf16 v[24:27], v[142:145], v[216:219], v[24:27]
	v_mfma_f32_16x16x32_bf16 v[16:19], v[154:157], v[216:219], v[16:19]
	v_mfma_f32_16x16x32_bf16 v[60:63], v[150:153], v[196:199], v[60:63]
	v_mfma_f32_16x16x32_bf16 v[56:59], v[158:161], v[196:199], v[56:59]
	v_mfma_f32_16x16x32_bf16 v[52:55], v[150:153], v[204:207], v[52:55]
	v_mfma_f32_16x16x32_bf16 v[48:51], v[158:161], v[204:207], v[48:51]
	v_mfma_f32_16x16x32_bf16 v[40:43], v[150:153], v[212:215], v[40:43]
	v_mfma_f32_16x16x32_bf16 v[32:35], v[158:161], v[212:215], v[32:35]
	v_mfma_f32_16x16x32_bf16 v[24:27], v[150:153], v[220:223], v[24:27]
	v_mfma_f32_16x16x32_bf16 v[16:19], v[158:161], v[220:223], v[16:19]
	s_setprio 0
	s_setprio 1
	v_mfma_f32_16x16x32_bf16 v[44:47], v[162:165], v[180:183], v[44:47]
	v_mfma_f32_16x16x32_bf16 v[36:39], v[170:173], v[180:183], v[36:39]
	v_mfma_f32_16x16x32_bf16 v[28:31], v[162:165], v[200:203], v[28:31]
	v_mfma_f32_16x16x32_bf16 v[20:23], v[170:173], v[200:203], v[20:23]
	v_mfma_f32_16x16x32_bf16 v[12:15], v[162:165], v[208:211], v[12:15]
	v_mfma_f32_16x16x32_bf16 v[8:11], v[170:173], v[208:211], v[8:11]
	v_mfma_f32_16x16x32_bf16 v[4:7], v[162:165], v[216:219], v[4:7]
	v_mfma_f32_16x16x32_bf16 v[0:3], v[170:173], v[216:219], v[0:3]
	v_mfma_f32_16x16x32_bf16 v[44:47], v[166:169], v[196:199], v[44:47]
	v_mfma_f32_16x16x32_bf16 v[36:39], v[174:177], v[196:199], v[36:39]
	v_mfma_f32_16x16x32_bf16 v[28:31], v[166:169], v[204:207], v[28:31]
	v_mfma_f32_16x16x32_bf16 v[20:23], v[174:177], v[204:207], v[20:23]
	v_mfma_f32_16x16x32_bf16 v[12:15], v[166:169], v[212:215], v[12:15]
	v_mfma_f32_16x16x32_bf16 v[8:11], v[174:177], v[212:215], v[8:11]
	v_mfma_f32_16x16x32_bf16 v[4:7], v[166:169], v[220:223], v[4:7]
	v_mfma_f32_16x16x32_bf16 v[0:3], v[174:177], v[220:223], v[0:3]
	s_setprio 0
	s_barrier
	s_add_u32 s91, s91, 0x100
	s_addc_u32 vcc_lo, vcc_lo, 0
	s_add_u32 s18, s18, 0x100
	s_addc_u32 s19, s19, 0
	s_cmp_ge_i32 vcc_hi, s82
	s_mov_b32 s20, vcc_hi
	s_cbranch_scc0 .LBB0_788
	s_add_i32 s8, s79, s41
	s_mov_b32 s8, 0x39b504f3
	v_pk_mul_f32 v[128:129], v[128:129], s[8:9] op_sel_hi:[1,0]
	v_pk_mul_f32 v[126:127], v[126:127], s[8:9] op_sel_hi:[1,0]
	v_pk_mul_f32 v[124:125], v[124:125], s[8:9] op_sel_hi:[1,0]
	v_pk_mul_f32 v[122:123], v[122:123], s[8:9] op_sel_hi:[1,0]
	v_pk_mul_f32 v[142:143], v[112:113], s[8:9] op_sel_hi:[1,0]
	v_pk_mul_f32 v[144:145], v[110:111], s[8:9] op_sel_hi:[1,0]
	v_pk_mul_f32 v[152:153], v[104:105], s[8:9] op_sel_hi:[1,0]
	v_pk_mul_f32 v[154:155], v[102:103], s[8:9] op_sel_hi:[1,0]
	v_pk_mul_f32 v[102:103], v[120:121], s[8:9] op_sel_hi:[1,0]
	v_pk_mul_f32 v[104:105], v[118:119], s[8:9] op_sel_hi:[1,0]
	v_pk_mul_f32 v[110:111], v[116:117], s[8:9] op_sel_hi:[1,0]
	v_pk_mul_f32 v[112:113], v[114:115], s[8:9] op_sel_hi:[1,0]
	v_pk_mul_f32 v[114:115], v[94:95], s[8:9] op_sel_hi:[1,0]
	v_pk_mul_f32 v[116:117], v[92:93], s[8:9] op_sel_hi:[1,0]
	v_pk_mul_f32 v[118:119], v[86:87], s[8:9] op_sel_hi:[1,0]
	v_pk_mul_f32 v[120:121], v[84:85], s[8:9] op_sel_hi:[1,0]
	v_pk_mul_f32 v[84:85], v[108:109], s[8:9] op_sel_hi:[1,0]
	v_pk_mul_f32 v[86:87], v[106:107], s[8:9] op_sel_hi:[1,0]
	v_pk_mul_f32 v[92:93], v[100:101], s[8:9] op_sel_hi:[1,0]
	v_pk_mul_f32 v[94:95], v[98:99], s[8:9] op_sel_hi:[1,0]
	v_pk_mul_f32 v[98:99], v[78:79], s[8:9] op_sel_hi:[1,0]
	v_pk_mul_f32 v[100:101], v[76:77], s[8:9] op_sel_hi:[1,0]
	v_pk_mul_f32 v[106:107], v[74:75], s[8:9] op_sel_hi:[1,0]
	v_pk_mul_f32 v[108:109], v[72:73], s[8:9] op_sel_hi:[1,0]
	v_pk_mul_f32 v[72:73], v[90:91], s[8:9] op_sel_hi:[1,0]
	v_pk_mul_f32 v[74:75], v[88:89], s[8:9] op_sel_hi:[1,0]
	v_pk_mul_f32 v[76:77], v[82:83], s[8:9] op_sel_hi:[1,0]
	v_pk_mul_f32 v[78:79], v[80:81], s[8:9] op_sel_hi:[1,0]
	v_pk_mul_f32 v[70:71], v[70:71], s[8:9] op_sel_hi:[1,0]
	v_pk_mul_f32 v[68:69], v[68:69], s[8:9] op_sel_hi:[1,0]
	v_pk_mul_f32 v[66:67], v[66:67], s[8:9] op_sel_hi:[1,0]
	v_pk_mul_f32 v[64:65], v[64:65], s[8:9] op_sel_hi:[1,0]
	v_pk_mul_f32 v[62:63], v[62:63], s[8:9] op_sel_hi:[1,0]
	v_pk_mul_f32 v[60:61], v[60:61], s[8:9] op_sel_hi:[1,0]
	v_pk_mul_f32 v[58:59], v[58:59], s[8:9] op_sel_hi:[1,0]
	v_pk_mul_f32 v[56:57], v[56:57], s[8:9] op_sel_hi:[1,0]
	v_pk_mul_f32 v[80:81], v[46:47], s[8:9] op_sel_hi:[1,0]
	v_pk_mul_f32 v[82:83], v[44:45], s[8:9] op_sel_hi:[1,0]
	v_pk_mul_f32 v[88:89], v[38:39], s[8:9] op_sel_hi:[1,0]
	v_pk_mul_f32 v[90:91], v[36:37], s[8:9] op_sel_hi:[1,0]
	v_pk_mul_f32 v[36:37], v[54:55], s[8:9] op_sel_hi:[1,0]
	v_pk_mul_f32 v[38:39], v[52:53], s[8:9] op_sel_hi:[1,0]
	v_pk_mul_f32 v[44:45], v[50:51], s[8:9] op_sel_hi:[1,0]
	v_pk_mul_f32 v[46:47], v[48:49], s[8:9] op_sel_hi:[1,0]
	v_pk_mul_f32 v[48:49], v[30:31], s[8:9] op_sel_hi:[1,0]
	v_pk_mul_f32 v[50:51], v[28:29], s[8:9] op_sel_hi:[1,0]
	v_pk_mul_f32 v[52:53], v[22:23], s[8:9] op_sel_hi:[1,0]
	v_pk_mul_f32 v[54:55], v[20:21], s[8:9] op_sel_hi:[1,0]
	v_pk_mul_f32 v[20:21], v[42:43], s[8:9] op_sel_hi:[1,0]
	v_pk_mul_f32 v[22:23], v[40:41], s[8:9] op_sel_hi:[1,0]
	v_pk_mul_f32 v[28:29], v[34:35], s[8:9] op_sel_hi:[1,0]
	v_pk_mul_f32 v[30:31], v[32:33], s[8:9] op_sel_hi:[1,0]
	v_pk_mul_f32 v[32:33], v[14:15], s[8:9] op_sel_hi:[1,0]
	v_pk_mul_f32 v[34:35], v[12:13], s[8:9] op_sel_hi:[1,0]
	v_pk_mul_f32 v[40:41], v[10:11], s[8:9] op_sel_hi:[1,0]
	v_pk_mul_f32 v[42:43], v[8:9], s[8:9] op_sel_hi:[1,0]
	v_pk_mul_f32 v[8:9], v[26:27], s[8:9] op_sel_hi:[1,0]
	v_pk_mul_f32 v[10:11], v[24:25], s[8:9] op_sel_hi:[1,0]
	v_pk_mul_f32 v[12:13], v[18:19], s[8:9] op_sel_hi:[1,0]
	v_pk_mul_f32 v[14:15], v[16:17], s[8:9] op_sel_hi:[1,0]
	v_pk_mul_f32 v[6:7], v[6:7], s[8:9] op_sel_hi:[1,0]
	v_pk_mul_f32 v[4:5], v[4:5], s[8:9] op_sel_hi:[1,0]
	v_pk_mul_f32 v[2:3], v[2:3], s[8:9] op_sel_hi:[1,0]
	v_pk_mul_f32 v[0:1], v[0:1], s[8:9] op_sel_hi:[1,0]
